# P4: third ret_out_item copy (8 early-mq workgroups) staging/gate loads batched
# speedup vs baseline: 1.0068x; 1.0007x over previous
.LBB0_794:
	s_or_b64 exec, exec, s[0:1]
	ds_read_b128 v[82:85], v78 offset:36864
	ds_read_b128 v[86:89], v78 offset:36928
	s_lshl_b32 s0, s88, 6
	v_lshlrev_b64 v[98:99], 9, v[38:39]
	s_lshl_b32 s2, s0, 1
	v_lshl_add_u64 v[170:171], v[98:99], 1, s[96:97]
	v_mov_b32_e32 v168, v36
	v_mov_b32_e32 v169, 0
	v_lshl_add_u64 v[170:171], v[170:171], 0, s[2:3]
	v_lshl_add_u64 v[170:171], v[170:171], 0, v[168:169]
	global_load_dwordx2 v[160:161], v[170:171], off nt
	global_load_dwordx2 v[162:163], v[170:171], off offset:32 nt
	global_load_dwordx2 v[164:165], v[170:171], off offset:64 nt
	global_load_dwordx2 v[166:167], v[170:171], off offset:96 nt
	s_mov_b64 s[0:1], 0x119a4400
	s_addk_i32 s86, 0x80
	s_waitcnt lgkmcnt(1)
	v_mfma_f32_16x16x32_bf16 v[82:85], v[82:85], v[4:7], 0
	ds_read_b128 v[90:93], v78 offset:39232
	ds_read_b128 v[94:97], v78 offset:41536
	s_waitcnt lgkmcnt(2)
	v_mfma_f32_16x16x32_bf16 v[82:85], v[86:89], v[0:3], v[82:85]
	ds_read_b128 v[86:89], v78 offset:39168
	s_waitcnt lgkmcnt(0)
	v_mfma_f32_16x16x32_bf16 v[86:89], v[86:89], v[4:7], 0
	v_mfma_f32_16x16x32_bf16 v[86:89], v[90:93], v[0:3], v[86:89]
	ds_read_b128 v[90:93], v78 offset:41472
	s_waitcnt lgkmcnt(0)
	v_mfma_f32_16x16x32_bf16 v[90:93], v[90:93], v[4:7], 0
	v_mfma_f32_16x16x32_bf16 v[90:93], v[94:97], v[0:3], v[90:93]
	ds_read_b128 v[94:97], v78 offset:43776
	s_waitcnt lgkmcnt(0)
	v_mfma_f32_16x16x32_bf16 v[4:7], v[94:97], v[4:7], 0
	ds_read_b128 v[94:97], v78 offset:43840
	s_waitcnt lgkmcnt(0)
	v_mfma_f32_16x16x32_bf16 v[2:5], v[94:97], v[0:3], v[4:7]
	v_mul_f32_e32 v0, v37, v73
	s_nop 3
	v_exp_f32_e32 v6, v0
	v_mov_b32_e32 v37, v25
	v_pk_fma_f32 v[22:23], v[6:7], v[84:85], v[22:23] op_sel_hi:[0,1,1]
	v_pk_fma_f32 v[20:21], v[6:7], v[82:83], v[20:21] op_sel_hi:[0,1,1]
	v_pk_mul_f32 v[0:1], v[22:23], v[22:23]
	v_pk_mul_f32 v[82:83], v[20:21], v[20:21]
	v_pk_fma_f32 v[14:15], v[6:7], v[88:89], v[14:15] op_sel_hi:[0,1,1]
	v_pk_mov_b32 v[84:85], v[82:83], v[0:1] op_sel:[1,0]
	v_mov_b32_e32 v83, v1
	v_pk_fma_f32 v[12:13], v[6:7], v[86:87], v[12:13] op_sel_hi:[0,1,1]
	v_pk_add_f32 v[82:83], v[84:85], v[82:83]
	v_pk_mul_f32 v[0:1], v[14:15], v[14:15]
	v_pk_mul_f32 v[84:85], v[12:13], v[12:13]
	v_pk_fma_f32 v[2:3], v[6:7], v[2:3], v[16:17] op_sel_hi:[0,1,1]
	v_pk_mov_b32 v[86:87], v[84:85], v[0:1] op_sel:[1,0]
	v_mov_b32_e32 v85, v1
	v_pk_add_f32 v[84:85], v[86:87], v[84:85]
	v_pk_fma_f32 v[10:11], v[6:7], v[92:93], v[10:11] op_sel_hi:[0,1,1]
	v_pk_fma_f32 v[8:9], v[6:7], v[90:91], v[8:9] op_sel_hi:[0,1,1]
	v_pk_fma_f32 v[0:1], v[6:7], v[4:5], v[18:19] op_sel_hi:[0,1,1]
	v_mul_f32_e32 v6, v2, v2
	v_pk_add_f32 v[4:5], v[82:83], v[82:83] op_sel:[0,1] op_sel_hi:[1,0]
	v_mul_f32_e32 v16, v3, v3
	v_mov_b32_e32 v5, v6
	v_pk_add_f32 v[6:7], v[84:85], v[84:85] op_sel:[0,1] op_sel_hi:[1,0]
	v_mul_f32_e32 v17, v0, v0
	v_mov_b32_e32 v7, v16
	v_pk_add_f32 v[4:5], v[4:5], v[6:7]
	v_mul_f32_e32 v6, v9, v9
	v_pk_fma_f32 v[6:7], v[8:9], v[8:9], v[6:7] op_sel_hi:[1,1,0]
	v_mul_f32_e32 v16, v11, v11
	v_mul_f32_e32 v18, v1, v1
	v_mov_b32_e32 v7, v17
	v_pk_fma_f32 v[16:17], v[10:11], v[10:11], v[16:17] op_sel_hi:[1,1,0]
	s_nop 0
	v_mov_b32_e32 v17, v18
	v_pk_add_f32 v[6:7], v[6:7], v[16:17]
	s_nop 0
	v_pk_add_f32 v[4:5], v[4:5], v[6:7]
	v_lshl_add_u64 v[6:7], v[98:99], 1, s[96:97]
	v_lshl_add_u64 v[6:7], v[6:7], 0, s[2:3]
	v_lshl_add_u64 v[16:17], v[6:7], 0, v[36:37]
	v_lshlrev_b64 v[6:7], 11, v[38:39]
	s_nop 0
	v_add_f32_e32 v4, v4, v5
	ds_bpermute_b32 v5, v131, v4
	v_lshl_add_u64 v[6:7], s[22:23], 0, v[6:7]
	v_lshl_add_u64 v[6:7], v[6:7], 0, s[2:3]
	v_lshl_add_u64 v[18:19], v[6:7], 0, v[36:37]
	v_lshl_add_u64 v[6:7], v[18:19], 0, s[0:1]
	s_waitcnt lgkmcnt(0)
	v_add_f32_e32 v4, v4, v5
	ds_bpermute_b32 v5, v134, v4
	s_mov_b32 s0, 0x119a4000
	v_add_co_u32_e64 v18, s[0:1], s0, v18
	s_add_i32 s2, s87, 1
	s_waitcnt lgkmcnt(0)
	v_add_f32_e32 v4, v4, v5
	v_fmamk_f32 v4, v4, 0x3c800000, v79
	v_rsq_f32_e32 v4, v4
	v_addc_co_u32_e64 v19, s[0:1], 0, v19, s[0:1]
	s_mov_b64 s[0:1], 0x2000
	v_pk_mul_f32 v[20:21], v[20:21], v[4:5] op_sel_hi:[1,0]
	v_pk_mul_f32 v[22:23], v[22:23], v[4:5] op_sel_hi:[1,0]
	v_pk_mul_f32 v[12:13], v[12:13], v[4:5] op_sel_hi:[1,0]
	v_pk_mul_f32 v[14:15], v[14:15], v[4:5] op_sel_hi:[1,0]
	v_pk_mul_f32 v[8:9], v[8:9], v[4:5] op_sel_hi:[1,0]
	v_pk_mul_f32 v[10:11], v[10:11], v[4:5] op_sel_hi:[1,0]
	v_pk_mul_f32 v[2:3], v[2:3], v[4:5] op_sel_hi:[1,0]
	v_pk_mul_f32 v[0:1], v[0:1], v[4:5] op_sel_hi:[1,0]
	v_lshl_add_u64 v[32:33], v[32:33], 0, s[0:1]
	s_cmp_ge_i32 s87, s33
	s_mov_b32 s87, s2
	s_waitcnt vmcnt(0)
	v_mov_b32_e32 v38, v160
	v_mov_b32_e32 v39, v161
	v_lshlrev_b32_e32 v82, 16, v38
	v_and_b32_e32 v83, 0xffff0000, v38
	v_lshlrev_b32_e32 v38, 16, v39
	v_and_b32_e32 v39, 0xffff0000, v39
	v_pk_mul_f32 v[20:21], v[20:21], v[82:83]
	v_pk_mul_f32 v[22:23], v[22:23], v[38:39]
	v_cvt_pk_bf16_f32 v20, v20, v21
	v_cvt_pk_bf16_f32 v21, v22, v23
	global_store_dwordx2 v[18:19], v[20:21], off offset:1024
	s_nop 1
	v_mov_b32_e32 v18, v162
	v_mov_b32_e32 v19, v163
	v_lshlrev_b32_e32 v20, 16, v18
	v_and_b32_e32 v21, 0xffff0000, v18
	v_lshlrev_b32_e32 v18, 16, v19
	v_and_b32_e32 v19, 0xffff0000, v19
	v_pk_mul_f32 v[12:13], v[12:13], v[20:21]
	v_pk_mul_f32 v[14:15], v[14:15], v[18:19]
	v_cvt_pk_bf16_f32 v12, v12, v13
	v_cvt_pk_bf16_f32 v13, v14, v15
	global_store_dwordx2 v[6:7], v[12:13], off offset:32
	s_nop 1
	v_mov_b32_e32 v12, v164
	v_mov_b32_e32 v13, v165
	v_lshlrev_b32_e32 v14, 16, v12
	v_and_b32_e32 v15, 0xffff0000, v12
	v_lshlrev_b32_e32 v12, 16, v13
	v_and_b32_e32 v13, 0xffff0000, v13
	v_pk_mul_f32 v[8:9], v[8:9], v[14:15]
	v_pk_mul_f32 v[10:11], v[10:11], v[12:13]
	v_cvt_pk_bf16_f32 v8, v8, v9
	v_cvt_pk_bf16_f32 v9, v10, v11
	global_store_dwordx2 v[6:7], v[8:9], off offset:64
	s_nop 1
	v_mov_b32_e32 v8, v166
	v_mov_b32_e32 v9, v167
	v_lshlrev_b32_e32 v10, 16, v8
	v_and_b32_e32 v11, 0xffff0000, v8
	v_lshlrev_b32_e32 v4, 16, v9
	v_and_b32_e32 v5, 0xffff0000, v9
	v_pk_mul_f32 v[2:3], v[2:3], v[10:11]
	v_pk_mul_f32 v[0:1], v[0:1], v[4:5]
	v_cvt_pk_bf16_f32 v2, v2, v3
	v_cvt_pk_bf16_f32 v3, v0, v1
	global_store_dwordx2 v[6:7], v[2:3], off offset:96
	s_cbranch_scc1 .LBB0_815
.LBB0_795:
	s_bfe_u32 s88, s87, 0x30005
	v_cvt_f32_ubyte0_e32 v0, s88
	v_sub_f32_e32 v0, 0xc0a00000, v0
	s_mov_b32 s0, 0xc2fc0000
	v_cmp_gt_f32_e64 s[0:1], s0, v0
	s_lshr_b32 s2, s87, 8
	s_nop 0
	v_cndmask_b32_e64 v1, 0, v74, s[0:1]
	v_add_f32_e32 v0, v0, v1
	v_exp_f32_e32 v0, v0
	s_and_b64 s[0:1], s[0:1], exec
	s_cselect_b32 s0, 0xffffffc0, 0
	s_and_b32 s89, s86, 0xf80
	v_ldexp_f32 v0, v0, s0
	s_lshl_b64 s[0:1], s[2:3], 12
	s_or_b32 s90, s0, s89
	v_sub_f32_e32 v10, 1.0, v0
	s_lshl_b32 s2, s88, 7
	v_mov_b32_e32 v1, s1
	v_or_b32_e32 v0, s90, v128
	v_lshl_add_u64 v[4:5], v[28:29], 0, s[2:3]
	v_lshlrev_b64 v[8:9], 10, v[0:1]
	v_lshl_add_u64 v[0:1], v[4:5], 0, v[8:9]
	global_load_dwordx4 v[140:143], v[0:1], off nt
	v_lshl_add_u64 v[6:7], v[30:31], 0, s[2:3]
	s_mov_b32 s91, s1
	v_add_u32_e32 v24, s89, v40
	v_lshl_add_u64 v[38:39], s[0:1], 0, v[24:25]
	v_log_f32_e32 v37, v10
	v_lshl_add_u64 v[0:1], v[6:7], 0, v[8:9]
	global_load_dwordx4 v[144:147], v[0:1], off nt
	v_lshl_add_u64 v[0:1], s[90:91], 0, v[26:27]
	v_lshlrev_b64 v[8:9], 10, v[0:1]
	v_lshl_add_u64 v[0:1], v[4:5], 0, v[8:9]
	global_load_dwordx4 v[148:151], v[0:1], off nt
	v_lshl_add_u64 v[0:1], v[6:7], 0, v[8:9]
	global_load_dwordx4 v[152:155], v[0:1], off nt
	global_load_dwordx4 v[156:159], v[32:33], off nt
	v_lshlrev_b64 v[0:1], 10, v[38:39]
	v_lshl_add_u64 v[0:1], s[94:95], 0, v[0:1]
	v_lshl_add_u64 v[0:1], v[0:1], 0, s[2:3]
	v_lshl_add_u64 v[0:1], v[0:1], 0, v[34:35]
	global_load_dwordx4 v[4:7], v[0:1], off nt
	s_nop 0
	global_load_dwordx4 v[0:3], v[0:1], off offset:64 nt
	s_barrier
	s_waitcnt vmcnt(6)
	ds_write_b128 v75, v[140:143]
	s_waitcnt vmcnt(5)
	ds_write_b128 v75, v[144:147] offset:18432
	s_waitcnt vmcnt(4)
	ds_write_b128 v76, v[148:151]
	s_waitcnt vmcnt(3)
	ds_write_b128 v76, v[152:155] offset:18432
	s_waitcnt vmcnt(2)
	ds_write_b128 v77, v[156:159] offset:36864
	s_waitcnt lgkmcnt(0)
	s_barrier
	ds_read_b128 v[8:11], v78
	ds_read_b128 v[12:15], v78 offset:64
	s_waitcnt vmcnt(1) lgkmcnt(1)
	v_mfma_f32_16x16x32_bf16 v[8:11], v[8:11], v[4:7], 0
	s_waitcnt vmcnt(0) lgkmcnt(0)
	v_mfma_f32_16x16x32_bf16 v[8:11], v[12:15], v[0:3], v[8:11]
	v_mov_b32_e32 v12, 0
	v_mov_b32_e32 v13, 0
	v_mov_b32_e32 v14, 0
	v_mov_b32_e32 v15, 0
	s_and_saveexec_b64 s[0:1], s[10:11]
	s_cbranch_execz .LBB0_797
	ds_read_b128 v[12:15], v78 offset:2304
	ds_read_b128 v[16:19], v78 offset:2368
	s_waitcnt lgkmcnt(1)
	v_mfma_f32_16x16x32_bf16 v[12:15], v[12:15], v[4:7], 0
	s_waitcnt lgkmcnt(0)
	v_mfma_f32_16x16x32_bf16 v[12:15], v[16:19], v[0:3], v[12:15]
	v_mul_f32_e32 v16, v37, v45
	v_mul_f32_e32 v17, v37, v46
	v_mul_f32_e32 v18, v37, v47
	v_mul_f32_e32 v19, v37, v48
	v_exp_f32_e32 v16, v16
	v_exp_f32_e32 v17, v17
	v_exp_f32_e32 v18, v18
	v_exp_f32_e32 v19, v19
	v_pk_mul_f32 v[12:13], v[16:17], v[12:13]
	s_nop 0
	v_cndmask_b32_e64 v12, 0, v12, s[30:31]
	v_pk_mul_f32 v[14:15], v[18:19], v[14:15]
	v_cndmask_b32_e64 v13, 0, v13, s[28:29]
	v_cndmask_b32_e64 v14, 0, v14, s[26:27]
	v_cndmask_b32_e64 v15, 0, v15, s[24:25]
